# attention A: persistent K/V tile pointers (fewer address VALU per step); plus earlier attention A mask-wait deferral and attention B cndmask-free PV
# speedup vs baseline: 1.0284x; 1.0284x over previous
; #define GAS __attribute__((address_space(1)))
; __device__ __forceinline__ int opaque_tid() { int t = threadIdx.x; asm volatile("" : "+v"(t)); return t; }
; __device__ void attn_pair_block(LAS unsigned char* lds, const bf16_t* Qp, const bf16_t* Kp, const bf16_t* Vp, int qb, bf16_t* outp, const float negMB) {
;     const int tid = opaque_tid(), wid = __builtin_amdgcn_readfirstlane(tid >> 6), lane = tid & 63, c = lane & 31, h = lane >> 5;
;     const int stw = wid >> 2;
;     const int q0 = qb * 128 + (wid & 3) * 32, qpos = q0 + c;
;     bf16x8 qf[8];
; #pragma unroll
;     for (int ks = 0; ks < 8; ++ks) qf[ks] = *(const GAS bf16x8*)(Qp + (size_t)qpos * 1024 + ks * 16 + h * 8);
;     f32x16 o[4];
; #pragma unroll
;     for (int d = 0; d < 4; ++d)
; #pragma unroll
;         for (int r = 0; r < 16; ++r) o[d][r] = 0.f;
;     float lrun = 0.f;
;     const int nt = 2 * (qb + 1);
;     const int my_last = (q0 + 31) >> 6;
;     u32x4 kr[2], vr[4];
;     ...
;     PB_GLOAD(0); PB_LSTORE(0);
; __global__ void __launch_bounds__(512, 2) mega(Params p_unused) {
;     ...
;         const int qx = item >> 16, n = item & 0xFFFF;
;         if (n < 256) {
;             const int qb = 127 - (n >> 1), map = n & 1, b = qx & 1, hb = qx >> 1;
;             const size_t tok0 = (size_t)b * SEQ;
;             const bf16_t* Q = (const bf16_t*)(p.ws + WS_QB) + tok0 * 1024 + (hb * 2 + map) * 128;
;             const bf16_t* K = (const bf16_t*)(p.ws + WS_KB) + tok0 * 1024 + (hb * 2 + map) * 128;
;             const bf16_t* V = (const bf16_t*)(p.ws + WS_VB) + tok0 * 1024 + hb * 256;
;             bf16_t* O = (bf16_t*)(dout + DO_OB) + tok0 * 2048 + (hb * 2 + map) * 256;
;             attn_pair_block(lds, Q, K, V, qb, O, negMB_b);
.LBB0_803:
	s_and_b64 vcc, exec, s[4:5]
	s_cbranch_vccz .LBB0_615
	s_lshr_b32 s4, s83, 1
	s_lshr_b32 s6, s82, 17
	s_sub_i32 s16, 0x7f, s4
	s_and_b32 s8, s82, 1
	s_lshl_b32 s4, s84, 14
	s_lshl_b32 s5, s6, 1
	s_and_b32 s11, s4, 0x4000
	s_or_b32 s10, s5, s8
	s_lshl_b32 s4, s11, 11
	s_lshl_b32 s5, s10, 8
	s_add_u32 s7, s50, s4
	s_addc_u32 s9, s51, 0
	v_and_b32_e32 v50, 64, v214
	v_lshlrev_b32_e32 v50, 2, v50
	v_lshrrev_b32_e32 v51, 1, v214
	v_and_b32_e32 v51, 0xc0, v51
	v_or_b32_e32 v50, v50, v51
	v_and_b32_e32 v51, 63, v214
	v_or_b32_e32 v50, v50, v51
	s_add_u32 s4, s7, s5
	s_addc_u32 s5, s9, 0
	v_lshlrev_b32_e32 v28, 4, v50
	v_and_b32_e32 v40, 0xf0, v28
	v_mov_b32_e32 v41, v155
	v_ashrrev_i32_e32 v42, 4, v50
	v_add_u32_e32 v29, 0x200, v50
	s_lshl_b32 s23, s6, 9
	v_lshl_add_u64 v[16:17], s[4:5], 0, v[40:41]
	v_ashrrev_i32_e32 v43, 31, v42
	v_ashrrev_i32_e32 v160, 4, v29
	s_add_u32 s6, s7, s23
	v_lshl_add_u64 v[158:159], v[16:17], 0, s[58:59]
	v_lshlrev_b64 v[44:45], 11, v[42:43]
	v_ashrrev_i32_e32 v161, 31, v160
	s_addc_u32 s7, s9, 0
	v_lshl_add_u64 v[24:25], v[158:159], 0, v[44:45]
	v_lshlrev_b64 v[16:17], 11, v[160:161]
	v_and_b32_e32 v162, 0x1f0, v28
	v_mov_b32_e32 v163, v155
	v_ashrrev_i32_e32 v166, 5, v50
	v_lshl_add_u64 v[26:27], v[158:159], 0, v[16:17]
	global_load_dwordx4 v[16:19], v[24:25], off
	global_load_dwordx4 v[20:23], v[26:27], off
	v_lshl_add_u64 v[24:25], s[6:7], 0, v[162:163]
	v_ashrrev_i32_e32 v167, 31, v166
	v_ashrrev_i32_e32 v168, 5, v29
	v_lshl_add_u64 v[164:165], v[24:25], 0, s[60:61]
	v_lshlrev_b64 v[24:25], 11, v[166:167]
	v_ashrrev_i32_e32 v169, 31, v168
	v_readfirstlane_b32 s6, v50
	v_lshl_add_u64 v[32:33], v[164:165], 0, v[24:25]
	v_lshlrev_b64 v[24:25], 11, v[168:169]
	s_ashr_i32 s7, s6, 6
	v_lshl_add_u64 v[34:35], v[164:165], 0, v[24:25]
	global_load_dwordx4 v[24:27], v[32:33], off
	global_load_dwordx4 v[28:31], v[34:35], off
	v_add_u32_e32 v32, 0x400, v50
	v_add_u32_e32 v36, 0x600, v50
	s_lshl_b32 s12, s7, 5
	v_ashrrev_i32_e32 v170, 5, v32
	v_ashrrev_i32_e32 v172, 5, v36
	s_lshl_b32 s9, s16, 7
	s_and_b32 s12, s12, 0x60
	v_ashrrev_i32_e32 v171, 31, v170
	v_ashrrev_i32_e32 v173, 31, v172
	v_and_b32_e32 v43, 31, v50
	s_or_b32 s18, s12, s9
	v_lshlrev_b64 v[32:33], 11, v[170:171]
	v_lshlrev_b64 v[36:37], 11, v[172:173]
	v_or_b32_e32 v156, s18, v43
	v_lshl_add_u64 v[32:33], v[164:165], 0, v[32:33]
	v_lshl_add_u64 v[36:37], v[164:165], 0, v[36:37]
	v_bfe_u32 v51, v50, 5, 1
	v_lshlrev_b32_e32 v154, 11, v156
	global_load_dwordx4 v[32:35], v[32:33], off
	v_lshl_add_u64 v[46:47], s[4:5], 0, v[154:155]
	global_load_dwordx4 v[36:39], v[36:37], off
	v_lshlrev_b32_e32 v154, 4, v51
	v_lshl_add_u64 v[46:47], v[46:47], 0, v[154:155]
	v_lshl_add_u64 v[48:49], v[46:47], 0, s[56:57]
	v_add_co_u32_e32 v46, vcc, s78, v46
	v_add_u32_e32 v185, 0, v40
	s_nop 0
	v_addc_co_u32_e32 v47, vcc, 0, v47, vcc
	global_load_dwordx4 v[120:123], v[48:49], off offset:32
	global_load_dwordx4 v[116:119], v[48:49], off offset:64
	global_load_dwordx4 v[112:115], v[48:49], off offset:96
	global_load_dwordx4 v[108:111], v[48:49], off offset:128
	global_load_dwordx4 v[100:103], v[48:49], off offset:160
	global_load_dwordx4 v[104:107], v[48:49], off offset:192
	global_load_dwordx4 v[124:127], v[46:47], off
	global_load_dwordx4 v[96:99], v[48:49], off offset:224
	v_mul_lo_u32 v186, v42, s79
	v_add_u32_e32 v40, v185, v186
	v_mul_lo_u32 v187, v160, s79
	v_mul_lo_u32 v188, v166, s80
	s_lshl_b32 s4, s7, 11
	s_ashr_i32 s12, s6, 8
	v_mul_lo_u32 v189, v168, s80
	s_add_i32 s13, s81, s4
	s_xor_b32 s4, s4, 0x2000
	v_mul_lo_u32 v190, v170, s80
	v_mul_lo_u32 v191, v172, s80
	s_lshr_b32 s21, s18, 6
	s_lshl_b32 s19, s12, 5
	s_and_b32 s14, s6, 0xffffff00
	s_add_i32 s15, s81, s4
	s_cmpk_lt_u32 s6, 0x100
	s_cselect_b64 s[6:7], -1, 0
	s_cmp_eq_u32 s12, 1
	v_lshlrev_b32_e32 v161, 2, v51
	s_cselect_b64 s[4:5], -1, 0
	s_and_b32 s9, s83, 0xfffe
	s_sub_i32 s22, 0xff, s9
	s_lshl_b32 s9, s82, 9
	s_lshl_b32 s8, s8, 8
	s_and_b32 s54, s9, 0x2000000
	s_or_b32 s8, s8, s23
	s_add_u32 s8, s50, s8
	s_addc_u32 s9, s51, 0
	v_and_b32_e32 v41, 63, v50
	v_lshlrev_b32_e32 v46, 3, v50
	v_and_b32_e32 v173, 24, v46
	v_lshlrev_b32_e32 v163, 4, v41
	s_mov_b32 s17, 63
	s_mov_b32 s20, 0
	v_sub_u32_e32 v183, v156, v161
	v_mov_b32_e32 v167, 0
	s_waitcnt vmcnt(13)
; #define LAS __attribute__((address_space(3)))
; __device__ void attn_pair_block(LAS unsigned char* lds, const bf16_t* Qp, const bf16_t* Kp, const bf16_t* Vp, int qb, bf16_t* outp, const float negMB) {
;     ...
;     f32x16 o[4];
; #pragma unroll
;     for (int d = 0; d < 4; ++d)
; #pragma unroll
;         for (int r = 0; r < 16; ++r) o[d][r] = 0.f;
;     float lrun = 0.f;
;     const int nt = 2 * (qb + 1);
;     const int my_last = (q0 + 31) >> 6;
;     u32x4 kr[2], vr[4];
;     ...
;     PB_GLOAD(0); PB_LSTORE(0);
;     __syncthreads();
;     const int kread = (32 * stw + c) * KP + h * 16;
;     const int vread = (4 * h + ((lane & 15) >> 2)) * VP2 + stw * 256 + ((lane >> 4) & 1) * 32 + (lane & 3) * 8;
;     LAS unsigned char* xmine = lds + XBUF_OFF + wid * 2048 + lane * 16;
;     const LAS unsigned char* xother = lds + XBUF_OFF + (wid ^ 4) * 2048 + lane * 16;
;     for (int j = 0; j < nt; ++j) {
;         LAS unsigned char* kb = lds + (j & 1) * PSTAGE; LAS unsigned char* vb = kb + KBYTES;
;         if (j + 1 < nt) PB_GLOAD(j + 1);
	ds_write_b128 v40, v[16:19]
	v_add_u32_e32 v16, v185, v187
	s_waitcnt vmcnt(12)
	ds_write_b128 v16, v[20:23]
	v_add_u32_e32 v16, 0, v162
	v_add_u32_e32 v17, v16, v188
	v_and_b32_e32 v18, 15, v50
	v_mov_b32_e32 v19, v155
	v_mov_b32_e32 v20, v155
	v_mov_b32_e32 v21, v155
	v_mov_b32_e32 v22, v155
	v_mov_b32_e32 v23, v155
	s_waitcnt vmcnt(11)
	ds_write_b128 v17, v[24:27] offset:17408
	v_add_u32_e32 v17, v16, v189
	s_waitcnt vmcnt(10)
	ds_write_b128 v17, v[28:31] offset:17408
	v_add_u32_e32 v17, v16, v190
	v_add_u32_e32 v16, v16, v191
	v_mov_b32_e32 v30, v155
	v_mov_b32_e32 v31, v155
	v_mov_b32_e32 v24, v155
	v_mov_b32_e32 v25, v155
	v_mov_b32_e32 v26, v155
	v_mov_b32_e32 v27, v155
	v_mov_b32_e32 v28, v155
	v_mov_b32_e32 v29, v155
	s_waitcnt vmcnt(9)
	ds_write_b128 v17, v[32:35] offset:17408
	s_waitcnt vmcnt(8)
	ds_write_b128 v16, v[36:39] offset:17408
	v_or_b32_e32 v16, s19, v43
	v_mul_lo_u32 v192, v16, s79
	v_lshrrev_b32_e32 v16, 2, v50
	v_and_or_b32 v16, v16, 3, v161
	v_mul_u32_u24_e32 v169, 0x240, v16
	v_lshlrev_b32_e32 v16, 1, v50
	v_and_b32_e32 v171, 32, v16
	v_lshl_add_u64 v[16:17], s[54:55], 0, v[44:45]
	v_lshl_or_b32 v16, v18, 4, v16
	v_lshl_add_u64 v[16:17], s[8:9], 0, v[16:17]
	v_lshl_add_u64 v[174:175], v[16:17], 0, s[62:63]
	v_mov_b32_e32 v16, v155
	v_mov_b32_e32 v17, v155
	v_mov_b32_e32 v18, v155
	v_mov_b64_e32 v[46:47], v[30:31]
	v_mov_b64_e32 v[62:63], v[30:31]
	v_mov_b64_e32 v[78:79], v[30:31]
	v_mov_b64_e32 v[44:45], v[28:29]
	v_mov_b64_e32 v[42:43], v[26:27]
	v_mov_b64_e32 v[40:41], v[24:25]
	v_mov_b64_e32 v[38:39], v[22:23]
	v_mov_b64_e32 v[36:37], v[20:21]
	v_mov_b64_e32 v[34:35], v[18:19]
	v_mov_b64_e32 v[32:33], v[16:17]
	v_mov_b64_e32 v[60:61], v[28:29]
	v_mov_b64_e32 v[58:59], v[26:27]
	v_mov_b64_e32 v[56:57], v[24:25]
	v_mov_b64_e32 v[54:55], v[22:23]
	v_mov_b64_e32 v[52:53], v[20:21]
	v_mov_b64_e32 v[50:51], v[18:19]
	v_mov_b64_e32 v[48:49], v[16:17]
	v_mov_b64_e32 v[76:77], v[28:29]
	v_mov_b64_e32 v[74:75], v[26:27]
	v_mov_b64_e32 v[72:73], v[24:25]
	v_mov_b64_e32 v[70:71], v[22:23]
	v_mov_b64_e32 v[68:69], v[20:21]
	v_mov_b64_e32 v[66:67], v[18:19]
	v_mov_b64_e32 v[64:65], v[16:17]
	v_add3_u32 v88, v160, s17, 1
	v_ashrrev_i32_e32 v89, 31, v88
	v_lshlrev_b64 v[88:89], 11, v[88:89]
	v_lshl_add_u64 v[88:89], v[158:159], 0, v[88:89]
	global_load_dwordx4 v[128:131], v[174:175], off
	global_load_dwordx4 v[136:139], v[88:89], off
	v_lshl_add_u64 v[174:175], v[174:175], 0, s[64:65]
	v_lshl_add_u64 v[254:255], v[88:89], 0, s[64:65]
	v_add3_u32 v90, v166, s17, 1
	v_ashrrev_i32_e32 v91, 31, v90
	v_lshlrev_b64 v[90:91], 11, v[90:91]
	v_lshl_add_u64 v[246:247], v[164:165], 0, v[90:91]
	v_add3_u32 v90, v168, s17, 1
	v_ashrrev_i32_e32 v91, 31, v90
	v_lshlrev_b64 v[90:91], 11, v[90:91]
	v_lshl_add_u64 v[248:249], v[164:165], 0, v[90:91]
	v_add3_u32 v90, v170, s17, 1
	v_ashrrev_i32_e32 v91, 31, v90
	v_lshlrev_b64 v[90:91], 11, v[90:91]
	v_lshl_add_u64 v[250:251], v[164:165], 0, v[90:91]
	v_add3_u32 v90, v172, s17, 1
	v_ashrrev_i32_e32 v91, 31, v90
	v_lshlrev_b64 v[90:91], 11, v[90:91]
	v_lshl_add_u64 v[252:253], v[164:165], 0, v[90:91]
	s_waitcnt vmcnt(2)
	s_waitcnt lgkmcnt(0)
	s_barrier
	s_branch .LBB0_806

; #define LAS __attribute__((address_space(3)))
; __device__ void attn_pair_block(LAS unsigned char* lds, const bf16_t* Qp, const bf16_t* Kp, const bf16_t* Vp, int qb, bf16_t* outp, const float negMB) {
;     ...
;     for (int j = 0; j < nt; ++j) {
;         LAS unsigned char* kb = lds + (j & 1) * PSTAGE; LAS unsigned char* vb = kb + KBYTES;
;         if (j + 1 < nt) PB_GLOAD(j + 1);
;         const bool act = j <= my_last;
;         bf16x8 pown[2];
;         if (act) {
;             f32x16 s0;
; #pragma unroll
;             for (int r = 0; r < 16; ++r) s0[r] = negMB;
; #pragma unroll
;             for (int ks = 0; ks < 8; ++ks) { const bf16x8 k0 = *(const LAS bf16x8*)(kb + kread + ks * 32); s0 = __builtin_amdgcn_mfma_f32_32x32x16_bf16(k0, qf[ks], s0, 0, 0, 0); }
;             __builtin_amdgcn_sched_group_barrier(0x100, 3, 0);
; #pragma unroll
;             for (int i = 0; i < 8; ++i) { __builtin_amdgcn_sched_group_barrier(0x008, 1, 0); __builtin_amdgcn_sched_group_barrier(0x100, 1, 0); }
;             if (j * 64 + 63 > q0) {
;                 const int kbase = j * 64 + 32 * stw + 4 * h;
; #pragma unroll
;                 for (int r = 0; r < 16; ++r) { const int key = kbase + (r & 3) + 8 * (r >> 2); if (key > qpos) s0[r] = -INFINITY; }
.LBB0_806:
	global_load_dwordx4 v[132:135], v[246:247], off
	global_load_dwordx4 v[144:147], v[248:249], off
	global_load_dwordx4 v[140:143], v[250:251], off
	global_load_dwordx4 v[148:151], v[252:253], off
	v_lshl_add_u64 v[246:247], v[246:247], 0, s[64:65]
	v_lshl_add_u64 v[248:249], v[248:249], 0, s[64:65]
	v_lshl_add_u64 v[250:251], v[250:251], 0, s[64:65]
	v_lshl_add_u64 v[252:253], v[252:253], 0, s[64:65]
	s_bitcmp1_b32 s20, 0
	s_cselect_b32 s8, 0xd400, 0
	s_add_i32 s23, s8, 0
	s_xor_b32 s24, s8, 0xd400
	v_add_u32_e32 v240, s24, v185
	v_add_u32_e32 v241, v240, v186
	v_add_u32_e32 v240, v240, v187
	s_waitcnt vmcnt(5)
	ds_write_b128 v241, v[128:131]
	s_waitcnt vmcnt(4)
	ds_write_b128 v240, v[136:139]
	s_cmp_le_u32 s20, s21
	s_cselect_b64 s[8:9], -1, 0
	s_cmp_gt_u32 s20, s21
	s_cbranch_scc1 .LBB0_810
	v_add3_u32 v193, s23, v192, v154
	ds_read_b128 v[194:197], v193
	ds_read_b128 v[198:201], v193 offset:32
	ds_read_b128 v[202:205], v193 offset:64
	s_cmp_le_u32 s17, s18
	s_waitcnt vmcnt(7) lgkmcnt(2)
	v_mfma_f32_32x32x16_bf16 v[80:95], v[194:197], v[124:127], v[0:15]
	ds_read_b128 v[194:197], v193 offset:96
	s_waitcnt lgkmcnt(2)
	v_mfma_f32_32x32x16_bf16 v[80:95], v[198:201], v[120:123], v[80:95]
	ds_read_b128 v[198:201], v193 offset:128
	s_waitcnt lgkmcnt(2)
	v_mfma_f32_32x32x16_bf16 v[80:95], v[202:205], v[116:119], v[80:95]
	ds_read_b128 v[202:205], v193 offset:160
	s_waitcnt lgkmcnt(2)
	v_mfma_f32_32x32x16_bf16 v[80:95], v[194:197], v[112:115], v[80:95]
	ds_read_b128 v[194:197], v193 offset:192
	s_waitcnt lgkmcnt(2)
	v_mfma_f32_32x32x16_bf16 v[80:95], v[198:201], v[108:111], v[80:95]
	ds_read_b128 v[198:201], v193 offset:224
	s_waitcnt lgkmcnt(2)
	v_mfma_f32_32x32x16_bf16 v[80:95], v[202:205], v[100:103], v[80:95]
	s_waitcnt lgkmcnt(1)
	v_mfma_f32_32x32x16_bf16 v[80:95], v[194:197], v[104:107], v[80:95]
	s_waitcnt vmcnt(6) lgkmcnt(0)
	v_mfma_f32_32x32x16_bf16 v[80:95], v[198:201], v[96:99], v[80:95]
	s_cbranch_scc1 .LBB0_809
	s_add_i32 s24, s19, s17
	s_sub_i32 s25, s24, 63
	v_cmp_lt_i32_e32 vcc, s25, v183
	s_nop 7
	v_cndmask_b32_e32 v81, v182, v81, vcc
	v_cmp_le_i32_e32 vcc, s25, v183
	s_sub_i32 s25, s24, 61
	s_nop 0
	v_cndmask_b32_e32 v80, v182, v80, vcc
	v_cmp_le_i32_e32 vcc, s25, v183
	s_sub_i32 s25, s24, 60
	s_nop 0
	v_cndmask_b32_e32 v82, v182, v82, vcc
	v_cmp_le_i32_e32 vcc, s25, v183
	s_sub_i32 s25, s24, 55
	s_nop 0
	v_cndmask_b32_e32 v83, v182, v83, vcc
	v_cmp_le_i32_e32 vcc, s25, v183
	s_sub_i32 s25, s24, 54
	s_nop 0
	v_cndmask_b32_e32 v84, v182, v84, vcc
	v_cmp_le_i32_e32 vcc, s25, v183
	s_sub_i32 s25, s24, 53
	s_nop 0
	v_cndmask_b32_e32 v85, v182, v85, vcc
	v_cmp_le_i32_e32 vcc, s25, v183
	s_sub_i32 s25, s24, 52
	s_nop 0
	v_cndmask_b32_e32 v86, v182, v86, vcc
	v_cmp_le_i32_e32 vcc, s25, v183
	s_sub_i32 s25, s24, 47
	s_nop 0
	v_cndmask_b32_e32 v87, v182, v87, vcc
	v_cmp_le_i32_e32 vcc, s25, v183
	s_sub_i32 s25, s24, 46
	s_nop 0
	v_cndmask_b32_e32 v88, v182, v88, vcc
	v_cmp_le_i32_e32 vcc, s25, v183
	s_sub_i32 s25, s24, 45
	s_nop 0
	v_cndmask_b32_e32 v89, v182, v89, vcc
	v_cmp_le_i32_e32 vcc, s25, v183
	s_sub_i32 s25, s24, 44
	s_nop 0
	v_cndmask_b32_e32 v90, v182, v90, vcc
	v_cmp_le_i32_e32 vcc, s25, v183
	s_sub_i32 s25, s24, 39
	s_nop 0
	v_cndmask_b32_e32 v91, v182, v91, vcc
	v_cmp_le_i32_e32 vcc, s25, v183
	s_sub_i32 s25, s24, 38
	s_nop 0
	v_cndmask_b32_e32 v92, v182, v92, vcc
	v_cmp_le_i32_e32 vcc, s25, v183
	s_sub_i32 s25, s24, 37
	s_sub_i32 s24, s24, 36
	v_cndmask_b32_e32 v93, v182, v93, vcc
	v_cmp_le_i32_e32 vcc, s25, v183
	s_nop 1
	v_cndmask_b32_e32 v94, v182, v94, vcc
	v_cmp_le_i32_e32 vcc, s24, v183
	s_nop 1
	v_cndmask_b32_e32 v95, v182, v95, vcc

; #define LAS __attribute__((address_space(3)))
; __device__ void attn_pair_block(LAS unsigned char* lds, const bf16_t* Qp, const bf16_t* Kp, const bf16_t* Vp, int qb, bf16_t* outp, const float negMB) {
;     ...
;         if (act) {
;             bf16x8 poth[2];
; #pragma unroll
;             for (int s2 = 0; s2 < 2; ++s2) poth[s2] = *(const LAS bf16x8*)(xother + s2 * 1024);
;             __builtin_amdgcn_s_setprio(1);
; #pragma unroll
;             for (int st = 0; st < 2; ++st)
; #pragma unroll
;                 for (int s2 = 0; s2 < 2; ++s2)
; #pragma unroll
;                     for (int d = 0; d < 4; ++d) {
;                         const s16x4 lo = __builtin_amdgcn_ds_read_tr16_b64_v4i16((LAS s16x4*)(vb + vread + (32 * st + 16 * s2) * VP2 + d * 64));
;                         const s16x4 hi = __builtin_amdgcn_ds_read_tr16_b64_v4i16((LAS s16x4*)(vb + vread + (32 * st + 16 * s2 + 8) * VP2 + d * 64));
;                         const bf16x8 vf = __builtin_shufflevector(lo, hi, 0, 1, 2, 3, 4, 5, 6, 7);
;                         const bf16x8 pfr = (st == stw) ? pown[s2] : poth[s2];
;                         o[d] = __builtin_amdgcn_mfma_f32_32x32x16_bf16(vf, pfr, o[d], 0, 0, 0);
;                     }
;             __builtin_amdgcn_sched_group_barrier(0x100, 8, 1);
; #pragma unroll
;             for (int i = 0; i < 16; ++i) { __builtin_amdgcn_sched_group_barrier(0x008, 1, 1); __builtin_amdgcn_sched_group_barrier(0x100, 2, 1); }
;             __builtin_amdgcn_s_setprio(0);
;         }
;         if (j + 1 < nt) PB_LSTORE((j + 1) & 1);
.LBB0_810:
	s_waitcnt lgkmcnt(0)
	s_barrier
	global_load_dwordx4 v[128:131], v[174:175], off
	global_load_dwordx4 v[136:139], v[254:255], off
	v_lshl_add_u64 v[254:255], v[254:255], 0, s[64:65]
	s_andn2_b64 vcc, exec, s[8:9]
	s_cbranch_vccnz .LBB0_805
	v_add_u32_e32 v92, s15, v163
	ds_read_b128 v[88:91], v92
	ds_read_b128 v[92:95], v92 offset:1024
	s_setprio 1
	s_add_i32 s8, s14, s23
	s_mul_i32 s24, s12, 0x4800
	s_sub_i32 s25, 0x4800, s24
	v_add_u32_e32 v193, s8, v169
	v_add3_u32 v193, v193, v171, v173
	v_add_u32_e32 v194, s25, v193
	v_add_u32_e32 v193, s24, v193
	ds_read_b64_tr_b16 v[198:199], v193 offset:17408
	ds_read_b64_tr_b16 v[200:201], v193 offset:22016
	ds_read_b64_tr_b16 v[202:203], v193 offset:17472
	ds_read_b64_tr_b16 v[204:205], v193 offset:22080
	ds_read_b64_tr_b16 v[206:207], v193 offset:17536
	ds_read_b64_tr_b16 v[208:209], v193 offset:22144
	ds_read_b64_tr_b16 v[210:211], v193 offset:17600
	ds_read_b64_tr_b16 v[212:213], v193 offset:22208
	s_add_i32 s24, s20, 1
	s_bitcmp1_b32 s24, 0
	s_cselect_b32 s23, 0xd400, 0
	v_add_u32_e32 v242, s23, v162
	v_add_u32_e32 v243, v242, v188
	v_add_u32_e32 v244, v242, v189
	v_add_u32_e32 v245, v242, v190
	v_add_u32_e32 v242, v242, v191
	s_waitcnt lgkmcnt(6)
	v_mfma_f32_32x32x16_bf16 v[64:79], v[198:201], v[84:87], v[64:79]
	ds_read_b64_tr_b16 v[198:199], v193 offset:26624
	ds_read_b64_tr_b16 v[200:201], v193 offset:31232
	s_waitcnt lgkmcnt(6)
	v_mfma_f32_32x32x16_bf16 v[48:63], v[202:205], v[84:87], v[48:63]
	ds_read_b64_tr_b16 v[202:203], v193 offset:26688
	ds_read_b64_tr_b16 v[204:205], v193 offset:31296
	s_waitcnt lgkmcnt(6)
	v_mfma_f32_32x32x16_bf16 v[32:47], v[206:209], v[84:87], v[32:47]
	ds_read_b64_tr_b16 v[206:207], v193 offset:26752
	ds_read_b64_tr_b16 v[208:209], v193 offset:31360
	s_waitcnt vmcnt(5)
	ds_write_b128 v243, v[132:135] offset:17408
	s_waitcnt lgkmcnt(7)
	v_mfma_f32_32x32x16_bf16 v[16:31], v[210:213], v[84:87], v[16:31]
	ds_read_b64_tr_b16 v[210:211], v193 offset:26816
	ds_read_b64_tr_b16 v[212:213], v193 offset:31424
	s_waitcnt lgkmcnt(7)
	v_mfma_f32_32x32x16_bf16 v[64:79], v[198:201], v[80:83], v[64:79]
	ds_read_b64_tr_b16 v[198:199], v194 offset:17408
	ds_read_b64_tr_b16 v[200:201], v194 offset:22016
	s_waitcnt lgkmcnt(7)
	v_mfma_f32_32x32x16_bf16 v[48:63], v[202:205], v[80:83], v[48:63]
	ds_read_b64_tr_b16 v[202:203], v194 offset:17472
	ds_read_b64_tr_b16 v[204:205], v194 offset:22080
	s_waitcnt vmcnt(4)
	ds_write_b128 v244, v[144:147] offset:17408
	s_waitcnt lgkmcnt(8)
	v_mfma_f32_32x32x16_bf16 v[32:47], v[206:209], v[80:83], v[32:47]
	ds_read_b64_tr_b16 v[206:207], v194 offset:17536
	ds_read_b64_tr_b16 v[208:209], v194 offset:22144
	s_waitcnt lgkmcnt(7)
	v_mfma_f32_32x32x16_bf16 v[16:31], v[210:213], v[80:83], v[16:31]
	ds_read_b64_tr_b16 v[210:211], v194 offset:17600
	ds_read_b64_tr_b16 v[212:213], v194 offset:22208
	s_waitcnt lgkmcnt(7)
	v_mfma_f32_32x32x16_bf16 v[64:79], v[198:201], v[88:91], v[64:79]
	ds_read_b64_tr_b16 v[198:199], v194 offset:26624
	ds_read_b64_tr_b16 v[200:201], v194 offset:31232
	s_waitcnt vmcnt(3)
	ds_write_b128 v245, v[140:143] offset:17408
	s_waitcnt lgkmcnt(8)
	v_mfma_f32_32x32x16_bf16 v[48:63], v[202:205], v[88:91], v[48:63]
	ds_read_b64_tr_b16 v[202:203], v194 offset:26688
	ds_read_b64_tr_b16 v[204:205], v194 offset:31296
	s_waitcnt lgkmcnt(7)
	v_mfma_f32_32x32x16_bf16 v[32:47], v[206:209], v[88:91], v[32:47]
	ds_read_b64_tr_b16 v[206:207], v194 offset:26752
	ds_read_b64_tr_b16 v[208:209], v194 offset:31360
	s_waitcnt lgkmcnt(7)
	v_mfma_f32_32x32x16_bf16 v[16:31], v[210:213], v[88:91], v[16:31]
	ds_read_b64_tr_b16 v[210:211], v194 offset:26816
	ds_read_b64_tr_b16 v[212:213], v194 offset:31424
	s_waitcnt vmcnt(2)
	ds_write_b128 v242, v[148:151] offset:17408
	s_waitcnt lgkmcnt(8)
	v_mfma_f32_32x32x16_bf16 v[64:79], v[198:201], v[92:95], v[64:79]
	s_waitcnt lgkmcnt(5)
	v_mfma_f32_32x32x16_bf16 v[48:63], v[202:205], v[92:95], v[48:63]
	s_waitcnt lgkmcnt(3)
	v_mfma_f32_32x32x16_bf16 v[32:47], v[206:209], v[92:95], v[32:47]
	s_waitcnt lgkmcnt(1)
	v_mfma_f32_32x32x16_bf16 v[16:31], v[210:213], v[92:95], v[16:31]
	s_setprio 0
	s_add_i32 s20, s20, 1
	s_branch .Lpb_tail

; __device__ __forceinline__ void lds_barrier() { asm volatile("s_waitcnt lgkmcnt(0)" ::: "memory"); __builtin_amdgcn_s_barrier(); asm volatile("" ::: "memory"); }
; #define ATT_GLOAD(j) do { _Pragma("unroll") for (int _i = 0; _i < 2; ++_i) { const size_t _o = (size_t)((j) * 64 + srow + 32 * _i) * 1024 + sch * 8; \
;         kr[_i] = *(const GAS u32x4*)(Kp + _o); vr[_i] = *(const GAS u32x4*)(Vp + _o); } } while (0)
; #define ATT_LSTORE(buf) do { _Pragma("unroll") for (int _i = 0; _i < 2; ++_i) { \
;         *(LAS u32x4*)(lds + (buf) * ASTAGE + (srow + 32 * _i) * KP + sch * 16) = kr[_i]; \
;         *(LAS u32x4*)(lds + (buf) * ASTAGE + KBYTES + (srow + 32 * _i) * VP + sch * 16) = vr[_i]; } } while (0)
; template <int MODE>
; __device__ void attn_block(LAS unsigned char* lds, const bf16_t* Qp, const bf16_t* Kp, const bf16_t* Vp, int qb, const unsigned* maskp, const bf16_t* sga, bf16_t* outp, const float negMB) {
;     ...
;     ATT_GLOAD(0); ATT_LSTORE(0);
;     const int kread = c * KP + h * 16;
;     const int vread = (4 * h + ((lane & 15) >> 2)) * VP + ((lane >> 4) & 1) * 32 + (lane & 3) * 8;
;     u32x4 mw4 = {0u, 0u, 0u, 0u};
;     int sj = 0, sp = 2;
;     for (int j = 0; j < nt; ++j) {
;         lds_barrier();
;         const int sn = (sj == 2) ? 0 : sj + 1;
;         if (j + 1 < nt) ATT_GLOAD(j + 1);
.LBB0_858:
	s_cmp_lg_u32 s50, 1
	s_cselect_b64 s[28:29], -1, 0
	s_lshl_b32 s8, s8, 2
	s_mov_b32 s34, 1
	s_add_i32 s53, s49, 4
	s_add_i32 s54, s51, 1
	s_waitcnt vmcnt(3)
	ds_write_b128 v194, v[148:151] offset:37888
	s_waitcnt vmcnt(2)
	ds_write_b128 v196, v[152:155] offset:55296
	s_waitcnt vmcnt(1)
	ds_write_b128 v194, v[160:163] offset:46592
	s_waitcnt vmcnt(0)
	ds_write_b128 v195, v[164:167] offset:55296
	v_or_b32_e32 v194, 2, v168
	v_or_b32_e32 v195, 3, v168
	v_or_b32_e32 v196, 8, v168
	v_or_b32_e32 v197, 9, v168
	v_or_b32_e32 v198, 10, v168
	v_or_b32_e32 v199, 11, v168
	v_or_b32_e32 v200, 16, v168
	v_or_b32_e32 v201, 17, v168
	v_or_b32_e32 v202, 18, v168
	v_or_b32_e32 v203, 19, v168
	v_or_b32_e32 v204, 24, v168
	v_or_b32_e32 v205, 25, v168
	v_or_b32_e32 v206, 26, v168
	v_or_b32_e32 v207, 27, v168
	v_add_u32_e32 v208, 0, v187
	s_mov_b32 s55, 0
	s_mov_b64 s[100:101], 0x20000
	v_add_u32_e32 v240, 0x80, v14
	v_ashrrev_i32_e32 v241, 31, v240
	v_lshlrev_b64 v[240:241], 11, v[240:241]
	v_lshlrev_b32_e32 v244, 1, v190
	v_or_b32_e32 v240, v240, v244
	v_lshl_add_u64 v[242:243], s[26:27], 0, v[240:241]
	v_lshl_add_u64 v[240:241], s[24:25], 0, v[240:241]
	v_add_u32_e32 v246, 0xa0, v14
	v_ashrrev_i32_e32 v247, 31, v246
	v_lshlrev_b64 v[246:247], 11, v[246:247]
	v_or_b32_e32 v246, v246, v244
	v_lshl_add_u64 v[244:245], s[24:25], 0, v[246:247]
	v_lshl_add_u64 v[246:247], s[26:27], 0, v[246:247]
	s_sub_i32 s56, 0, s8
	s_movk_i32 s57, 0xff01
	s_mov_b32 s60, 0
.LBB0_859:
	s_waitcnt lgkmcnt(0)
	s_barrier
	s_add_i32 s8, s57, 0x101
	s_cmp_lt_i32 s8, s53
	s_mov_b32 s58, s34
	s_cselect_b64 s[30:31], -1, 0
	s_cmp_ge_i32 s8, s53
	s_cbranch_scc1 .LBB0_861
	global_load_dwordx4 v[148:151], v[240:241], off
	global_load_dwordx4 v[152:155], v[242:243], off
	global_load_dwordx4 v[160:163], v[244:245], off
	global_load_dwordx4 v[164:167], v[246:247], off
	v_lshl_add_u64 v[240:241], v[240:241], 0, s[100:101]
	v_lshl_add_u64 v[242:243], v[242:243], 0, s[100:101]
	v_lshl_add_u64 v[244:245], v[244:245], 0, s[100:101]
	v_lshl_add_u64 v[246:247], v[246:247], 0, s[100:101]

; template <int MODE>
; __device__ void attn_block(LAS unsigned char* lds, const bf16_t* Qp, const bf16_t* Kp, const bf16_t* Vp, int qb, const unsigned* maskp, const bf16_t* sga, bf16_t* outp, const float negMB) {
;     ...
;         if (grp == 1 && j >= 1 && j - 1 <= my_last) ATT_PV(sp);
.LBB0_866:
.LBB0_867:
	s_cmp_gt_i32 s59, s54
	s_cselect_b64 s[34:35], -1, 0
	s_or_b64 s[34:35], s[28:29], s[34:35]
	s_and_b64 vcc, exec, s[34:35]
	s_cbranch_vccnz .LBB0_869
	s_mul_i32 s8, s60, 0x9400
	s_setprio 1
	v_add_u32_e32 v124, s8, v208
	ds_read_b64_tr_b16 v[112:113], v124 offset:17408
	ds_read_b64_tr_b16 v[114:115], v124 offset:19968
	ds_read_b64_tr_b16 v[116:117], v124 offset:17472
	ds_read_b64_tr_b16 v[118:119], v124 offset:20032
	ds_read_b64_tr_b16 v[120:121], v124 offset:17536
	ds_read_b64_tr_b16 v[122:123], v124 offset:20096
	s_waitcnt lgkmcnt(4)
	v_mfma_f32_32x32x16_bf16 v[80:95], v[112:115], v[104:107], v[80:95]
	ds_read_b64_tr_b16 v[112:113], v124 offset:17600
	ds_read_b64_tr_b16 v[114:115], v124 offset:20160
	s_waitcnt lgkmcnt(4)
	v_mfma_f32_32x32x16_bf16 v[64:79], v[116:119], v[104:107], v[64:79]
	ds_read_b64_tr_b16 v[116:117], v124 offset:22528
	ds_read_b64_tr_b16 v[118:119], v124 offset:25088
	s_waitcnt lgkmcnt(4)
	v_mfma_f32_32x32x16_bf16 v[48:63], v[120:123], v[104:107], v[48:63]
	ds_read_b64_tr_b16 v[120:121], v124 offset:22592
	ds_read_b64_tr_b16 v[122:123], v124 offset:25152
	s_waitcnt lgkmcnt(4)
	v_mfma_f32_32x32x16_bf16 v[32:47], v[112:115], v[104:107], v[32:47]
	ds_read_b64_tr_b16 v[112:113], v124 offset:22656
	ds_read_b64_tr_b16 v[114:115], v124 offset:25216
	s_waitcnt lgkmcnt(4)
	v_mfma_f32_32x32x16_bf16 v[80:95], v[116:119], v[108:111], v[80:95]
	ds_read_b64_tr_b16 v[116:117], v124 offset:22720
	ds_read_b64_tr_b16 v[118:119], v124 offset:25280
	s_waitcnt lgkmcnt(4)
	v_mfma_f32_32x32x16_bf16 v[64:79], v[120:123], v[108:111], v[64:79]
	ds_read_b64_tr_b16 v[120:121], v124 offset:27648
	ds_read_b64_tr_b16 v[122:123], v124 offset:30208
	s_waitcnt lgkmcnt(4)
	v_mfma_f32_32x32x16_bf16 v[48:63], v[112:115], v[108:111], v[48:63]
	ds_read_b64_tr_b16 v[112:113], v124 offset:27712
	ds_read_b64_tr_b16 v[114:115], v124 offset:30272
	s_waitcnt lgkmcnt(4)
	v_mfma_f32_32x32x16_bf16 v[32:47], v[116:119], v[108:111], v[32:47]
	ds_read_b64_tr_b16 v[116:117], v124 offset:27776
	ds_read_b64_tr_b16 v[118:119], v124 offset:30336
	s_waitcnt lgkmcnt(4)
	v_mfma_f32_32x32x16_bf16 v[80:95], v[120:123], v[100:103], v[80:95]
	ds_read_b64_tr_b16 v[120:121], v124 offset:27840
	ds_read_b64_tr_b16 v[122:123], v124 offset:30400
	s_waitcnt lgkmcnt(4)
	v_mfma_f32_32x32x16_bf16 v[64:79], v[112:115], v[100:103], v[64:79]
	ds_read_b64_tr_b16 v[112:113], v124 offset:32768
	ds_read_b64_tr_b16 v[114:115], v124 offset:35328
	s_waitcnt lgkmcnt(4)
	v_mfma_f32_32x32x16_bf16 v[48:63], v[116:119], v[100:103], v[48:63]
	ds_read_b64_tr_b16 v[116:117], v124 offset:32832
	ds_read_b64_tr_b16 v[118:119], v124 offset:35392
	s_waitcnt lgkmcnt(4)
	v_mfma_f32_32x32x16_bf16 v[32:47], v[120:123], v[100:103], v[32:47]
	ds_read_b64_tr_b16 v[120:121], v124 offset:32896
	ds_read_b64_tr_b16 v[122:123], v124 offset:35456
	s_waitcnt lgkmcnt(4)
	v_mfma_f32_32x32x16_bf16 v[80:95], v[112:115], v[96:99], v[80:95]
	ds_read_b64_tr_b16 v[112:113], v124 offset:32960
	ds_read_b64_tr_b16 v[114:115], v124 offset:35520
	s_waitcnt lgkmcnt(4)
	v_mfma_f32_32x32x16_bf16 v[64:79], v[116:119], v[96:99], v[64:79]
	s_waitcnt lgkmcnt(2)
	v_mfma_f32_32x32x16_bf16 v[48:63], v[120:123], v[96:99], v[48:63]
	s_waitcnt lgkmcnt(0)
	v_mfma_f32_32x32x16_bf16 v[32:47], v[112:115], v[96:99], v[32:47]
	s_setprio 0

; #define GAS __attribute__((address_space(1)))
; template <int MODE>
; __device__ void attn_block(LAS unsigned char* lds, const bf16_t* Qp, const bf16_t* Kp, const bf16_t* Vp, int qb, const unsigned* maskp, const bf16_t* sga, bf16_t* outp, const float negMB) {
;     ...
;         u32x2 mw = {0u, 0u};
;         if (MODE == 0) {
;             if ((j & 1) == 0) { if (j <= my_last) mw4 = *(const GAS u32x4*)(maskp + ((size_t)(j >> 1) * SEQ + qpos) * 4); mw.x = mw4.x; mw.y = mw4.y; }
;             else { mw.x = mw4.z; mw.y = mw4.w; }
;         }
.LBB0_872:
	s_bitcmp1_b32 s59, 0
	s_cbranch_scc1 .Lma_odd
	s_waitcnt vmcnt(0)
	v_mov_b32_e32 v176, v157
	v_mov_b32_e32 v177, v156

; #define LAS __attribute__((address_space(3)))
; __global__ void __launch_bounds__(512, 2) mega(Params p_unused) {
;     KQ kp = (KQ)__builtin_amdgcn_kernarg_segment_ptr();
;     extern __shared__ __attribute__((aligned(16))) unsigned char lds_raw[];
;     LAS unsigned char* lds = (LAS unsigned char*)lds_raw;
;     cg::grid_group grid = cg::this_grid();
	.amdhsa_kernel _Z4mega6Params
		.amdhsa_group_segment_fixed_size 0
		.amdhsa_private_segment_fixed_size 0
		.amdhsa_kernarg_size 400
		.amdhsa_user_sgpr_count 2
		.amdhsa_user_sgpr_dispatch_ptr 0
		.amdhsa_user_sgpr_queue_ptr 0
		.amdhsa_user_sgpr_kernarg_segment_ptr 1
		.amdhsa_user_sgpr_dispatch_id 0
		.amdhsa_user_sgpr_kernarg_preload_length 0
		.amdhsa_user_sgpr_kernarg_preload_offset 0
		.amdhsa_user_sgpr_private_segment_size 0
		.amdhsa_uses_dynamic_stack 0
		.amdhsa_enable_private_segment 0
		.amdhsa_system_sgpr_workgroup_id_x 1
		.amdhsa_system_sgpr_workgroup_id_y 0
		.amdhsa_system_sgpr_workgroup_id_z 0
		.amdhsa_system_sgpr_workgroup_info 0
		.amdhsa_system_vgpr_workitem_id 2
		.amdhsa_next_free_vgpr 256
		.amdhsa_next_free_sgpr 102
		.amdhsa_accum_offset 256
		.amdhsa_reserve_vcc 1
		.amdhsa_float_round_mode_32 0
		.amdhsa_float_round_mode_16_64 0
		.amdhsa_float_denorm_mode_32 3
		.amdhsa_float_denorm_mode_16_64 3
		.amdhsa_dx10_clamp 1
		.amdhsa_ieee_mode 1
		.amdhsa_fp16_overflow 0
		.amdhsa_tg_split 0
		.amdhsa_exception_fp_ieee_invalid_op 0
		.amdhsa_exception_fp_denorm_src 0
		.amdhsa_exception_fp_ieee_div_zero 0
		.amdhsa_exception_fp_ieee_overflow 0
		.amdhsa_exception_fp_ieee_underflow 0
		.amdhsa_exception_fp_ieee_inexact 0
		.amdhsa_exception_int_div_zero 0
	.end_amdhsa_kernel

; #define LAS __attribute__((address_space(3)))
; __global__ void __launch_bounds__(512, 2) mega(Params p_unused) {
;     KQ kp = (KQ)__builtin_amdgcn_kernarg_segment_ptr();
;     extern __shared__ __attribute__((aligned(16))) unsigned char lds_raw[];
;     LAS unsigned char* lds = (LAS unsigned char*)lds_raw;
amdhsa.kernels:
  - .agpr_count:     0
    .args:
      - .offset:         0
        .size:           144
        .value_kind:     by_value
      - .offset:         144
        .size:           4
        .value_kind:     hidden_block_count_x
      - .offset:         148
        .size:           4
        .value_kind:     hidden_block_count_y
      - .offset:         152
        .size:           4
        .value_kind:     hidden_block_count_z
      - .offset:         156
        .size:           2
        .value_kind:     hidden_group_size_x
      - .offset:         158
        .size:           2
        .value_kind:     hidden_group_size_y
      - .offset:         160
        .size:           2
        .value_kind:     hidden_group_size_z
      - .offset:         162
        .size:           2
        .value_kind:     hidden_remainder_x
      - .offset:         164
        .size:           2
        .value_kind:     hidden_remainder_y
      - .offset:         166
        .size:           2
        .value_kind:     hidden_remainder_z
      - .offset:         184
        .size:           8
        .value_kind:     hidden_global_offset_x
      - .offset:         192
        .size:           8
        .value_kind:     hidden_global_offset_y
      - .offset:         200
        .size:           8
        .value_kind:     hidden_global_offset_z
      - .offset:         208
        .size:           2
        .value_kind:     hidden_grid_dims
      - .offset:         232
        .size:           8
        .value_kind:     hidden_multigrid_sync_arg
      - .offset:         264
        .size:           4
        .value_kind:     hidden_dynamic_lds_size
    .group_segment_fixed_size: 0
    .kernarg_segment_align: 8
    .kernarg_segment_size: 400
    .language:       OpenCL C
    .language_version:
      - 2
      - 0
    .max_flat_workgroup_size: 512
    .name:           _Z4mega6Params
    .private_segment_fixed_size: 0
    .sgpr_count:     108
    .sgpr_spill_count: 0
    .symbol:         _Z4mega6Params.kd
    .uniform_work_group_size: 1
    .uses_dynamic_stack: false
    .vgpr_count:     256
    .vgpr_spill_count: 0
    .wavefront_size: 64
